# sample-side SSD step: z values preloaded per batch + v_readlane instead of a per-item load and vmcnt(0) drain; GEMM3 epilogue hand-rewritten (residual loads issued 16 at a time, counted vmcnt)
# speedup vs baseline: 1.0688x; 1.0054x over previous
.LBB0_396:
	s_waitcnt lgkmcnt(0)
	v_add_u32_e32 v195, s42, v73
	v_lshlrev_b32_e32 v195, 1, v195
	global_load_ushort v194, v195, s[6:7] offset:3072
	v_cmp_lt_u32_e64 s[100:101], 31, v73
	v_lshl_add_u32 v12, s12, 8, v86
	s_or_b32 s65, s12, 1
	v_ashrrev_i32_e32 v13, 31, v12
	v_lshl_add_u32 v14, s65, 8, v86
	v_lshl_add_u64 v[12:13], v[12:13], 2, v[76:77]
	v_ashrrev_i32_e32 v15, 31, v14
	v_lshl_add_u64 v[14:15], v[14:15], 2, v[76:77]
	global_load_dwordx4 v[96:99], v[12:13], off
	global_load_dwordx4 v[68:71], v[14:15], off
	s_or_b32 s64, s12, 2
	s_or_b32 s63, s12, 3
	v_lshl_add_u32 v12, s64, 8, v86
	v_lshl_add_u32 v14, s63, 8, v86
	v_ashrrev_i32_e32 v13, 31, v12
	v_ashrrev_i32_e32 v15, 31, v14
	v_lshl_add_u64 v[12:13], v[12:13], 2, v[76:77]
	v_lshl_add_u64 v[14:15], v[14:15], 2, v[76:77]
	s_or_b32 s62, s12, 4
	s_or_b32 s61, s12, 5
	global_load_dwordx4 v[64:67], v[12:13], off
	global_load_dwordx4 v[60:63], v[14:15], off
	v_lshl_add_u32 v12, s62, 8, v86
	v_lshl_add_u32 v14, s61, 8, v86
	v_ashrrev_i32_e32 v13, 31, v12
	v_ashrrev_i32_e32 v15, 31, v14
	v_lshl_add_u64 v[12:13], v[12:13], 2, v[76:77]
	v_lshl_add_u64 v[14:15], v[14:15], 2, v[76:77]
	s_or_b32 s60, s12, 6
	s_or_b32 s41, s12, 7
	global_load_dwordx4 v[56:59], v[12:13], off
	global_load_dwordx4 v[52:55], v[14:15], off
	v_lshl_add_u32 v12, s60, 8, v86
	v_lshl_add_u32 v14, s41, 8, v86
	v_ashrrev_i32_e32 v13, 31, v12
	v_ashrrev_i32_e32 v15, 31, v14
	v_lshl_add_u64 v[12:13], v[12:13], 2, v[76:77]
	v_lshl_add_u64 v[14:15], v[14:15], 2, v[76:77]
	s_or_b32 s40, s12, 8
	s_or_b32 s35, s12, 9
	global_load_dwordx4 v[48:51], v[12:13], off
	global_load_dwordx4 v[44:47], v[14:15], off
	v_lshl_add_u32 v12, s40, 8, v86
	v_lshl_add_u32 v14, s35, 8, v86
	v_ashrrev_i32_e32 v13, 31, v12
	v_ashrrev_i32_e32 v15, 31, v14
	v_lshl_add_u64 v[12:13], v[12:13], 2, v[76:77]
	v_lshl_add_u64 v[14:15], v[14:15], 2, v[76:77]
	s_or_b32 s34, s12, 10
	s_or_b32 s31, s12, 11
	global_load_dwordx4 v[40:43], v[12:13], off
	global_load_dwordx4 v[36:39], v[14:15], off
	v_lshl_add_u32 v12, s34, 8, v86
	v_lshl_add_u32 v14, s31, 8, v86
	v_ashrrev_i32_e32 v13, 31, v12
	v_ashrrev_i32_e32 v15, 31, v14
	v_lshl_add_u64 v[12:13], v[12:13], 2, v[76:77]
	v_lshl_add_u64 v[14:15], v[14:15], 2, v[76:77]
	s_or_b32 s30, s12, 12
	s_or_b32 s15, s12, 13
	global_load_dwordx4 v[32:35], v[12:13], off
	global_load_dwordx4 v[28:31], v[14:15], off
	v_lshl_add_u32 v12, s30, 8, v86
	v_lshl_add_u32 v14, s15, 8, v86
	v_ashrrev_i32_e32 v13, 31, v12
	v_ashrrev_i32_e32 v15, 31, v14
	v_lshl_add_u64 v[12:13], v[12:13], 2, v[76:77]
	v_lshl_add_u64 v[14:15], v[14:15], 2, v[76:77]
	s_or_b32 s14, s12, 14
	s_or_b32 s1, s12, 15
	global_load_dwordx4 v[24:27], v[12:13], off
	global_load_dwordx4 v[20:23], v[14:15], off
	v_lshl_add_u32 v12, s14, 8, v86
	v_lshl_add_u32 v14, s1, 8, v86
	v_ashrrev_i32_e32 v13, 31, v12
	v_ashrrev_i32_e32 v15, 31, v14
	v_lshl_add_u64 v[12:13], v[12:13], 2, v[76:77]
	v_lshl_add_u64 v[14:15], v[14:15], 2, v[76:77]
	global_load_dwordx4 v[16:19], v[12:13], off
	s_nop 0
	global_load_dwordx4 v[12:15], v[14:15], off
	v_lshl_add_u32 v82, s12, 1, v85
	v_lshl_add_u32 v1, v82, 2, s87
	ds_read_b32 v94, v1
	v_mov_b32_e32 v1, v0
	s_waitcnt lgkmcnt(0)
	v_mul_f32_e32 v100, v75, v94
	v_pk_mul_f32 v[102:103], v[4:5], v[100:101] op_sel_hi:[1,0]
	v_pk_mul_f32 v[100:101], v[6:7], v[100:101] op_sel_hi:[1,0]
	s_waitcnt vmcnt(15)
	v_pk_fma_f32 v[100:101], v[0:1], v[98:99], v[100:101]
	v_pk_fma_f32 v[98:99], v[78:79], v[96:97], v[102:103]
	v_mul_f32_e32 v95, v11, v101
	v_mul_f32_e32 v83, v9, v99
	v_fmac_f32_e32 v83, v8, v98
	v_fmac_f32_e32 v95, v10, v100
	v_add_f32_e32 v83, v83, v95
	ds_bpermute_b32 v95, v88, v83
	v_lshlrev_b32_e32 v102, 7, v82
	v_ashrrev_i32_e32 v103, 31, v102
	v_lshl_add_u64 v[102:103], v[102:103], 2, v[80:81]
	global_store_dwordx4 v[102:103], v[98:101], off
	s_waitcnt lgkmcnt(0)
	v_add_f32_e32 v83, v83, v95
	ds_bpermute_b32 v95, v89, v83
	s_waitcnt lgkmcnt(0)
	v_add_f32_e32 v83, v83, v95
	ds_bpermute_b32 v95, v90, v83
	s_waitcnt lgkmcnt(0)
	v_add_f32_e32 v83, v83, v95
	ds_bpermute_b32 v95, v91, v83
	s_waitcnt lgkmcnt(0)
	v_add_f32_e32 v95, v83, v95
	ds_bpermute_b32 v96, v92, v95
	s_and_saveexec_b64 s[12:13], s[2:3]
	s_cbranch_execz .LBB0_398
	v_ashrrev_i32_e32 v83, 31, v82
	v_lshl_add_u64 v[98:99], v[82:83], 0, s[42:43]
	v_lshl_add_u64 v[98:99], v[98:99], 1, s[6:7]
	v_readfirstlane_b32 s66, v82
	s_nop 3
	v_readlane_b32 s67, v194, s66
	s_add_i32 s66, s66, 1
	s_nop 1
	v_mov_b32_e32 v97, s67
	v_readlane_b32 s67, v194, s66
	s_nop 1
	v_mov_b32_e32 v196, s67
	v_cndmask_b32_e64 v97, v97, v196, s[100:101]
	s_waitcnt lgkmcnt(0)
	v_add_f32_e32 v95, v95, v96
	v_fmac_f32_e32 v95, v84, v94
	v_lshl_add_u64 v[82:83], v[82:83], 1, s[8:9]
	v_lshlrev_b32_e32 v97, 16, v97
	v_mul_f32_e32 v98, 0xbfb8aa3b, v97
	v_exp_f32_e32 v98, v98
	s_nop 0
	v_add_f32_e32 v96, 1.0, v98
	v_div_scale_f32 v98, s[66:67], v96, v96, v97
	v_rcp_f32_e32 v99, v98
	v_div_scale_f32 v94, vcc, v97, v96, v97
	v_fma_f32 v100, -v98, v99, 1.0
	v_fmac_f32_e32 v99, v100, v99
	v_mul_f32_e32 v100, v94, v99
	v_fma_f32 v101, -v98, v100, v94
	v_fmac_f32_e32 v100, v101, v99
	v_fma_f32 v94, -v98, v100, v94
	v_div_fmas_f32 v94, v94, v99, v100
	v_div_fixup_f32 v94, v94, v96, v97
	v_mul_f32_e32 v94, v95, v94
	v_fmac_f32_e32 v93, v94, v94
	v_cvt_pk_bf16_f32 v94, v94, s0
	global_store_short v[82:83], v94, off
.LBB0_398:
	s_or_b64 exec, exec, s[12:13]
	v_lshl_add_u32 v82, s65, 1, v85
	v_lshl_add_u32 v83, v82, 2, s87
	ds_read_b32 v94, v83
	s_waitcnt lgkmcnt(0)
	v_mul_f32_e32 v96, v75, v94
	v_pk_mul_f32 v[100:101], v[4:5], v[96:97] op_sel_hi:[1,0]
	v_pk_mul_f32 v[96:97], v[6:7], v[96:97] op_sel_hi:[1,0]
	s_waitcnt vmcnt(15)
	v_pk_fma_f32 v[98:99], v[0:1], v[70:71], v[96:97]
	v_pk_fma_f32 v[96:97], v[78:79], v[68:69], v[100:101]
	v_mul_f32_e32 v68, v11, v99
	v_mul_f32_e32 v1, v9, v97
	v_fmac_f32_e32 v1, v8, v96
	v_fmac_f32_e32 v68, v10, v98
	v_add_f32_e32 v1, v1, v68
	ds_bpermute_b32 v68, v88, v1
	v_lshlrev_b32_e32 v70, 7, v82
	v_ashrrev_i32_e32 v71, 31, v70
	v_lshl_add_u64 v[70:71], v[70:71], 2, v[80:81]
	global_store_dwordx4 v[70:71], v[96:99], off
	s_waitcnt lgkmcnt(0)
	v_add_f32_e32 v1, v1, v68
	ds_bpermute_b32 v68, v89, v1
	s_waitcnt lgkmcnt(0)
	v_add_f32_e32 v1, v1, v68
	ds_bpermute_b32 v68, v90, v1
	s_waitcnt lgkmcnt(0)
	v_add_f32_e32 v1, v1, v68
	ds_bpermute_b32 v68, v91, v1
	s_waitcnt lgkmcnt(0)
	v_add_f32_e32 v1, v1, v68
	ds_bpermute_b32 v68, v92, v1
	s_and_saveexec_b64 s[12:13], s[2:3]
	s_cbranch_execz .LBB0_400
	v_ashrrev_i32_e32 v83, 31, v82
	v_lshl_add_u64 v[70:71], v[82:83], 0, s[42:43]
	v_lshl_add_u64 v[70:71], v[70:71], 1, s[6:7]
	v_readfirstlane_b32 s66, v82
	s_nop 3
	v_readlane_b32 s67, v194, s66
	s_add_i32 s66, s66, 1
	s_nop 1
	v_mov_b32_e32 v69, s67
	v_readlane_b32 s67, v194, s66
	s_nop 1
	v_mov_b32_e32 v196, s67
	v_cndmask_b32_e64 v69, v69, v196, s[100:101]
	s_waitcnt lgkmcnt(0)
	v_add_f32_e32 v1, v1, v68
	v_fmac_f32_e32 v1, v84, v94
	v_lshlrev_b32_e32 v69, 16, v69
	v_mul_f32_e32 v70, 0xbfb8aa3b, v69
	v_exp_f32_e32 v70, v70
	s_nop 0
	v_add_f32_e32 v68, 1.0, v70
	v_div_scale_f32 v70, s[66:67], v68, v68, v69
	v_rcp_f32_e32 v71, v70
	v_div_scale_f32 v94, vcc, v69, v68, v69
	v_fma_f32 v95, -v70, v71, 1.0
	v_fmac_f32_e32 v71, v95, v71
	v_mul_f32_e32 v95, v94, v71
	v_fma_f32 v96, -v70, v95, v94
	v_fmac_f32_e32 v95, v96, v71
	v_fma_f32 v70, -v70, v95, v94
	v_div_fmas_f32 v70, v70, v71, v95
	v_div_fixup_f32 v68, v70, v68, v69
	v_mul_f32_e32 v1, v1, v68
	v_fmac_f32_e32 v93, v1, v1
	v_cvt_pk_bf16_f32 v1, v1, s0
	v_lshl_add_u64 v[68:69], v[82:83], 1, s[8:9]
	global_store_short v[68:69], v1, off
.LBB0_400:
	s_or_b64 exec, exec, s[12:13]
	s_waitcnt lgkmcnt(0)
	v_lshl_add_u32 v68, s64, 1, v85
	v_lshl_add_u32 v1, v68, 2, s87
	ds_read_b32 v70, v1
	v_mov_b32_e32 v1, v0
	s_waitcnt lgkmcnt(0)
	v_mul_f32_e32 v82, v75, v70
	v_pk_mul_f32 v[94:95], v[4:5], v[82:83] op_sel_hi:[1,0]
	v_pk_mul_f32 v[82:83], v[6:7], v[82:83] op_sel_hi:[1,0]
	s_waitcnt vmcnt(15)
	v_pk_fma_f32 v[94:95], v[78:79], v[64:65], v[94:95]
	v_pk_fma_f32 v[96:97], v[0:1], v[66:67], v[82:83]
	v_mul_f32_e32 v64, v9, v95
	v_mul_f32_e32 v65, v11, v97
	v_fmac_f32_e32 v64, v8, v94
	v_fmac_f32_e32 v65, v10, v96
	v_add_f32_e32 v64, v64, v65
	ds_bpermute_b32 v65, v88, v64
	v_lshlrev_b32_e32 v66, 7, v68
	v_ashrrev_i32_e32 v67, 31, v66
	v_lshl_add_u64 v[66:67], v[66:67], 2, v[80:81]
	global_store_dwordx4 v[66:67], v[94:97], off
	s_waitcnt lgkmcnt(0)
	v_add_f32_e32 v64, v64, v65
	ds_bpermute_b32 v65, v89, v64
	s_waitcnt lgkmcnt(0)
	v_add_f32_e32 v64, v64, v65
	ds_bpermute_b32 v65, v90, v64
	s_waitcnt lgkmcnt(0)
	v_add_f32_e32 v64, v64, v65
	ds_bpermute_b32 v65, v91, v64
	s_waitcnt lgkmcnt(0)
	v_add_f32_e32 v64, v64, v65
	ds_bpermute_b32 v65, v92, v64
	s_and_saveexec_b64 s[12:13], s[2:3]
	s_cbranch_execz .LBB0_402
	v_ashrrev_i32_e32 v69, 31, v68
	v_lshl_add_u64 v[66:67], v[68:69], 0, s[42:43]
	v_lshl_add_u64 v[66:67], v[66:67], 1, s[6:7]
	v_readfirstlane_b32 s64, v68
	s_nop 3
	v_readlane_b32 s65, v194, s64
	s_add_i32 s64, s64, 1
	s_nop 1
	v_mov_b32_e32 v66, s65
	v_readlane_b32 s65, v194, s64
	s_nop 1
	v_mov_b32_e32 v196, s65
	v_cndmask_b32_e64 v66, v66, v196, s[100:101]
	s_waitcnt lgkmcnt(0)
	v_add_f32_e32 v64, v64, v65
	v_fmac_f32_e32 v64, v84, v70
	v_lshlrev_b32_e32 v66, 16, v66
	v_mul_f32_e32 v67, 0xbfb8aa3b, v66
	v_exp_f32_e32 v67, v67
	s_nop 0
	v_add_f32_e32 v65, 1.0, v67
	v_div_scale_f32 v67, s[64:65], v65, v65, v66
	v_rcp_f32_e32 v71, v67
	v_div_scale_f32 v70, vcc, v66, v65, v66
	v_fma_f32 v82, -v67, v71, 1.0
	v_fmac_f32_e32 v71, v82, v71
	v_mul_f32_e32 v82, v70, v71
	v_fma_f32 v83, -v67, v82, v70
	v_fmac_f32_e32 v82, v83, v71
	v_fma_f32 v67, -v67, v82, v70
	v_div_fmas_f32 v67, v67, v71, v82
	v_div_fixup_f32 v65, v67, v65, v66
	v_mul_f32_e32 v64, v64, v65
	v_fmac_f32_e32 v93, v64, v64
	v_cvt_pk_bf16_f32 v66, v64, s0
	v_lshl_add_u64 v[64:65], v[68:69], 1, s[8:9]
	global_store_short v[64:65], v66, off
.LBB0_402:
	s_or_b64 exec, exec, s[12:13]
	v_lshl_add_u32 v64, s63, 1, v85
	s_waitcnt lgkmcnt(0)
	v_lshl_add_u32 v65, v64, 2, s87
	ds_read_b32 v66, v65
	s_waitcnt lgkmcnt(0)
	v_mul_f32_e32 v68, v75, v66
	v_pk_mul_f32 v[82:83], v[4:5], v[68:69] op_sel_hi:[1,0]
	v_pk_mul_f32 v[68:69], v[6:7], v[68:69] op_sel_hi:[1,0]
	s_waitcnt vmcnt(15)
	v_pk_fma_f32 v[70:71], v[0:1], v[62:63], v[68:69]
	v_pk_fma_f32 v[68:69], v[78:79], v[60:61], v[82:83]
	v_mul_f32_e32 v60, v11, v71
	v_mul_f32_e32 v1, v9, v69
	v_fmac_f32_e32 v1, v8, v68
	v_fmac_f32_e32 v60, v10, v70
	v_add_f32_e32 v1, v1, v60
	ds_bpermute_b32 v60, v88, v1
	v_lshlrev_b32_e32 v62, 7, v64
	v_ashrrev_i32_e32 v63, 31, v62
	v_lshl_add_u64 v[62:63], v[62:63], 2, v[80:81]
	global_store_dwordx4 v[62:63], v[68:71], off
	s_waitcnt lgkmcnt(0)
	v_add_f32_e32 v1, v1, v60
	ds_bpermute_b32 v60, v89, v1
	s_waitcnt lgkmcnt(0)
	v_add_f32_e32 v1, v1, v60
	ds_bpermute_b32 v60, v90, v1
	s_waitcnt lgkmcnt(0)
	v_add_f32_e32 v1, v1, v60
	ds_bpermute_b32 v60, v91, v1
	s_waitcnt lgkmcnt(0)
	v_add_f32_e32 v1, v1, v60
	ds_bpermute_b32 v60, v92, v1
	s_and_saveexec_b64 s[12:13], s[2:3]
	s_cbranch_execz .LBB0_404
	v_ashrrev_i32_e32 v65, 31, v64
	v_lshl_add_u64 v[62:63], v[64:65], 0, s[42:43]
	v_lshl_add_u64 v[62:63], v[62:63], 1, s[6:7]
	v_readfirstlane_b32 s64, v64
	s_nop 3
	v_readlane_b32 s65, v194, s64
	s_add_i32 s64, s64, 1
	s_nop 1
	v_mov_b32_e32 v61, s65
	v_readlane_b32 s65, v194, s64
	s_nop 1
	v_mov_b32_e32 v196, s65
	v_cndmask_b32_e64 v61, v61, v196, s[100:101]
	s_waitcnt lgkmcnt(0)
	v_add_f32_e32 v1, v1, v60
	v_fmac_f32_e32 v1, v84, v66
	v_lshlrev_b32_e32 v61, 16, v61
	v_mul_f32_e32 v62, 0xbfb8aa3b, v61
	v_exp_f32_e32 v62, v62
	s_nop 0
	v_add_f32_e32 v60, 1.0, v62
	v_div_scale_f32 v62, s[64:65], v60, v60, v61
	v_rcp_f32_e32 v63, v62
	v_div_scale_f32 v66, vcc, v61, v60, v61
	v_fma_f32 v67, -v62, v63, 1.0
	v_fmac_f32_e32 v63, v67, v63
	v_mul_f32_e32 v67, v66, v63
	v_fma_f32 v68, -v62, v67, v66
	v_fmac_f32_e32 v67, v68, v63
	v_fma_f32 v62, -v62, v67, v66
	v_div_fmas_f32 v62, v62, v63, v67
	v_div_fixup_f32 v60, v62, v60, v61
	v_mul_f32_e32 v1, v1, v60
	v_fmac_f32_e32 v93, v1, v1
	v_cvt_pk_bf16_f32 v1, v1, s0
	v_lshl_add_u64 v[60:61], v[64:65], 1, s[8:9]
	global_store_short v[60:61], v1, off
.LBB0_404:
	s_or_b64 exec, exec, s[12:13]
	s_waitcnt lgkmcnt(0)
	v_lshl_add_u32 v60, s62, 1, v85
	v_lshl_add_u32 v1, v60, 2, s87
	ds_read_b32 v62, v1
	v_mov_b32_e32 v1, v0
	s_waitcnt lgkmcnt(0)
	v_mul_f32_e32 v64, v75, v62
	v_pk_mul_f32 v[68:69], v[4:5], v[64:65] op_sel_hi:[1,0]
	v_pk_mul_f32 v[64:65], v[6:7], v[64:65] op_sel_hi:[1,0]
	s_waitcnt vmcnt(15)
	v_pk_fma_f32 v[66:67], v[0:1], v[58:59], v[64:65]
	v_pk_fma_f32 v[64:65], v[78:79], v[56:57], v[68:69]
	v_mul_f32_e32 v57, v11, v67
	v_mul_f32_e32 v56, v9, v65
	v_fmac_f32_e32 v56, v8, v64
	v_fmac_f32_e32 v57, v10, v66
	v_add_f32_e32 v56, v56, v57
	ds_bpermute_b32 v57, v88, v56
	v_lshlrev_b32_e32 v58, 7, v60
	v_ashrrev_i32_e32 v59, 31, v58
	v_lshl_add_u64 v[58:59], v[58:59], 2, v[80:81]
	global_store_dwordx4 v[58:59], v[64:67], off
	s_waitcnt lgkmcnt(0)
	v_add_f32_e32 v56, v56, v57
	ds_bpermute_b32 v57, v89, v56
	s_waitcnt lgkmcnt(0)
	v_add_f32_e32 v56, v56, v57
	ds_bpermute_b32 v57, v90, v56
	s_waitcnt lgkmcnt(0)
	v_add_f32_e32 v56, v56, v57
	ds_bpermute_b32 v57, v91, v56
	s_waitcnt lgkmcnt(0)
	v_add_f32_e32 v56, v56, v57
	ds_bpermute_b32 v57, v92, v56
	s_and_saveexec_b64 s[12:13], s[2:3]
	s_cbranch_execz .LBB0_406
	v_ashrrev_i32_e32 v61, 31, v60
	v_lshl_add_u64 v[58:59], v[60:61], 0, s[42:43]
	v_lshl_add_u64 v[58:59], v[58:59], 1, s[6:7]
	v_readfirstlane_b32 s62, v60
	s_nop 3
	v_readlane_b32 s63, v194, s62
	s_add_i32 s62, s62, 1
	s_nop 1
	v_mov_b32_e32 v58, s63
	v_readlane_b32 s63, v194, s62
	s_nop 1
	v_mov_b32_e32 v196, s63
	v_cndmask_b32_e64 v58, v58, v196, s[100:101]
	s_waitcnt lgkmcnt(0)
	v_add_f32_e32 v56, v56, v57
	v_fmac_f32_e32 v56, v84, v62
	v_lshlrev_b32_e32 v58, 16, v58
	v_mul_f32_e32 v59, 0xbfb8aa3b, v58
	v_exp_f32_e32 v59, v59
	s_nop 0
	v_add_f32_e32 v57, 1.0, v59
	v_div_scale_f32 v59, s[62:63], v57, v57, v58
	v_rcp_f32_e32 v63, v59
	v_div_scale_f32 v62, vcc, v58, v57, v58
	v_fma_f32 v64, -v59, v63, 1.0
	v_fmac_f32_e32 v63, v64, v63
	v_mul_f32_e32 v64, v62, v63
	v_fma_f32 v65, -v59, v64, v62
	v_fmac_f32_e32 v64, v65, v63
	v_fma_f32 v59, -v59, v64, v62
	v_div_fmas_f32 v59, v59, v63, v64
	v_div_fixup_f32 v57, v59, v57, v58
	v_mul_f32_e32 v56, v56, v57
	v_fmac_f32_e32 v93, v56, v56
	v_cvt_pk_bf16_f32 v58, v56, s0
	v_lshl_add_u64 v[56:57], v[60:61], 1, s[8:9]
	global_store_short v[56:57], v58, off
.LBB0_406:
	s_or_b64 exec, exec, s[12:13]
	v_lshl_add_u32 v56, s61, 1, v85
	s_waitcnt lgkmcnt(0)
	v_lshl_add_u32 v57, v56, 2, s87
	ds_read_b32 v58, v57
	s_waitcnt lgkmcnt(0)
	v_mul_f32_e32 v60, v75, v58
	v_pk_mul_f32 v[64:65], v[4:5], v[60:61] op_sel_hi:[1,0]
	v_pk_mul_f32 v[60:61], v[6:7], v[60:61] op_sel_hi:[1,0]
	s_waitcnt vmcnt(15)
	v_pk_fma_f32 v[62:63], v[0:1], v[54:55], v[60:61]
	v_pk_fma_f32 v[60:61], v[78:79], v[52:53], v[64:65]
	v_mul_f32_e32 v52, v11, v63
	v_mul_f32_e32 v1, v9, v61
	v_fmac_f32_e32 v1, v8, v60
	v_fmac_f32_e32 v52, v10, v62
	v_add_f32_e32 v1, v1, v52
	ds_bpermute_b32 v52, v88, v1
	v_lshlrev_b32_e32 v54, 7, v56
	v_ashrrev_i32_e32 v55, 31, v54
	v_lshl_add_u64 v[54:55], v[54:55], 2, v[80:81]
	global_store_dwordx4 v[54:55], v[60:63], off
	s_waitcnt lgkmcnt(0)
	v_add_f32_e32 v1, v1, v52
	ds_bpermute_b32 v52, v89, v1
	s_waitcnt lgkmcnt(0)
	v_add_f32_e32 v1, v1, v52
	ds_bpermute_b32 v52, v90, v1
	s_waitcnt lgkmcnt(0)
	v_add_f32_e32 v1, v1, v52
	ds_bpermute_b32 v52, v91, v1
	s_waitcnt lgkmcnt(0)
	v_add_f32_e32 v1, v1, v52
	ds_bpermute_b32 v52, v92, v1
	s_and_saveexec_b64 s[12:13], s[2:3]
	s_cbranch_execz .LBB0_408
	v_ashrrev_i32_e32 v57, 31, v56
	v_lshl_add_u64 v[54:55], v[56:57], 0, s[42:43]
	v_lshl_add_u64 v[54:55], v[54:55], 1, s[6:7]
	v_readfirstlane_b32 s62, v56
	s_nop 3
	v_readlane_b32 s63, v194, s62
	s_add_i32 s62, s62, 1
	s_nop 1
	v_mov_b32_e32 v53, s63
	v_readlane_b32 s63, v194, s62
	s_nop 1
	v_mov_b32_e32 v196, s63
	v_cndmask_b32_e64 v53, v53, v196, s[100:101]
	s_waitcnt lgkmcnt(0)
	v_add_f32_e32 v1, v1, v52
	v_fmac_f32_e32 v1, v84, v58
	v_lshlrev_b32_e32 v53, 16, v53
	v_mul_f32_e32 v54, 0xbfb8aa3b, v53
	v_exp_f32_e32 v54, v54
	s_nop 0
	v_add_f32_e32 v52, 1.0, v54
	v_div_scale_f32 v54, s[62:63], v52, v52, v53
	v_rcp_f32_e32 v55, v54
	v_div_scale_f32 v58, vcc, v53, v52, v53
	v_fma_f32 v59, -v54, v55, 1.0
	v_fmac_f32_e32 v55, v59, v55
	v_mul_f32_e32 v59, v58, v55
	v_fma_f32 v60, -v54, v59, v58
	v_fmac_f32_e32 v59, v60, v55
	v_fma_f32 v54, -v54, v59, v58
	v_div_fmas_f32 v54, v54, v55, v59
	v_div_fixup_f32 v52, v54, v52, v53
	v_mul_f32_e32 v1, v1, v52
	v_fmac_f32_e32 v93, v1, v1
	v_cvt_pk_bf16_f32 v1, v1, s0
	v_lshl_add_u64 v[52:53], v[56:57], 1, s[8:9]
	global_store_short v[52:53], v1, off
.LBB0_408:
	s_or_b64 exec, exec, s[12:13]
	s_waitcnt lgkmcnt(0)
	v_lshl_add_u32 v52, s60, 1, v85
	v_lshl_add_u32 v1, v52, 2, s87
	ds_read_b32 v54, v1
	v_mov_b32_e32 v1, v0
	s_waitcnt lgkmcnt(0)
	v_mul_f32_e32 v56, v75, v54
	v_pk_mul_f32 v[60:61], v[4:5], v[56:57] op_sel_hi:[1,0]
	v_pk_mul_f32 v[56:57], v[6:7], v[56:57] op_sel_hi:[1,0]
	s_waitcnt vmcnt(15)
	v_pk_fma_f32 v[58:59], v[0:1], v[50:51], v[56:57]
	v_pk_fma_f32 v[56:57], v[78:79], v[48:49], v[60:61]
	v_mul_f32_e32 v49, v11, v59
	v_mul_f32_e32 v48, v9, v57
	v_fmac_f32_e32 v48, v8, v56
	v_fmac_f32_e32 v49, v10, v58
	v_add_f32_e32 v48, v48, v49
	ds_bpermute_b32 v49, v88, v48
	v_lshlrev_b32_e32 v50, 7, v52
	v_ashrrev_i32_e32 v51, 31, v50
	v_lshl_add_u64 v[50:51], v[50:51], 2, v[80:81]
	global_store_dwordx4 v[50:51], v[56:59], off
	s_waitcnt lgkmcnt(0)
	v_add_f32_e32 v48, v48, v49
	ds_bpermute_b32 v49, v89, v48
	s_waitcnt lgkmcnt(0)
	v_add_f32_e32 v48, v48, v49
	ds_bpermute_b32 v49, v90, v48
	s_waitcnt lgkmcnt(0)
	v_add_f32_e32 v48, v48, v49
	ds_bpermute_b32 v49, v91, v48
	s_waitcnt lgkmcnt(0)
	v_add_f32_e32 v48, v48, v49
	ds_bpermute_b32 v49, v92, v48
	s_and_saveexec_b64 s[12:13], s[2:3]
	s_cbranch_execz .LBB0_410
	v_ashrrev_i32_e32 v53, 31, v52
	v_lshl_add_u64 v[50:51], v[52:53], 0, s[42:43]
	v_lshl_add_u64 v[50:51], v[50:51], 1, s[6:7]
	v_readfirstlane_b32 s60, v52
	s_nop 3
	v_readlane_b32 s61, v194, s60
	s_add_i32 s60, s60, 1
	s_nop 1
	v_mov_b32_e32 v50, s61
	v_readlane_b32 s61, v194, s60
	s_nop 1
	v_mov_b32_e32 v196, s61
	v_cndmask_b32_e64 v50, v50, v196, s[100:101]
	s_waitcnt lgkmcnt(0)
	v_add_f32_e32 v48, v48, v49
	v_fmac_f32_e32 v48, v84, v54
	v_lshlrev_b32_e32 v50, 16, v50
	v_mul_f32_e32 v51, 0xbfb8aa3b, v50
	v_exp_f32_e32 v51, v51
	s_nop 0
	v_add_f32_e32 v49, 1.0, v51
	v_div_scale_f32 v51, s[60:61], v49, v49, v50
	v_rcp_f32_e32 v55, v51
	v_div_scale_f32 v54, vcc, v50, v49, v50
	v_fma_f32 v56, -v51, v55, 1.0
	v_fmac_f32_e32 v55, v56, v55
	v_mul_f32_e32 v56, v54, v55
	v_fma_f32 v57, -v51, v56, v54
	v_fmac_f32_e32 v56, v57, v55
	v_fma_f32 v51, -v51, v56, v54
	v_div_fmas_f32 v51, v51, v55, v56
	v_div_fixup_f32 v49, v51, v49, v50
	v_mul_f32_e32 v48, v48, v49
	v_fmac_f32_e32 v93, v48, v48
	v_cvt_pk_bf16_f32 v50, v48, s0
	v_lshl_add_u64 v[48:49], v[52:53], 1, s[8:9]
	global_store_short v[48:49], v50, off
.LBB0_410:
	s_or_b64 exec, exec, s[12:13]
	v_lshl_add_u32 v48, s41, 1, v85
	s_waitcnt lgkmcnt(0)
	v_lshl_add_u32 v49, v48, 2, s87
	ds_read_b32 v50, v49
	s_waitcnt lgkmcnt(0)
	v_mul_f32_e32 v52, v75, v50
	v_pk_mul_f32 v[56:57], v[4:5], v[52:53] op_sel_hi:[1,0]
	v_pk_mul_f32 v[52:53], v[6:7], v[52:53] op_sel_hi:[1,0]
	s_waitcnt vmcnt(15)
	v_pk_fma_f32 v[54:55], v[0:1], v[46:47], v[52:53]
	v_pk_fma_f32 v[52:53], v[78:79], v[44:45], v[56:57]
	v_mul_f32_e32 v44, v11, v55
	v_mul_f32_e32 v1, v9, v53
	v_fmac_f32_e32 v1, v8, v52
	v_fmac_f32_e32 v44, v10, v54
	v_add_f32_e32 v1, v1, v44
	ds_bpermute_b32 v44, v88, v1
	v_lshlrev_b32_e32 v46, 7, v48
	v_ashrrev_i32_e32 v47, 31, v46
	v_lshl_add_u64 v[46:47], v[46:47], 2, v[80:81]
	global_store_dwordx4 v[46:47], v[52:55], off
	s_waitcnt lgkmcnt(0)
	v_add_f32_e32 v1, v1, v44
	ds_bpermute_b32 v44, v89, v1
	s_waitcnt lgkmcnt(0)
	v_add_f32_e32 v1, v1, v44
	ds_bpermute_b32 v44, v90, v1
	s_waitcnt lgkmcnt(0)
	v_add_f32_e32 v1, v1, v44
	ds_bpermute_b32 v44, v91, v1
	s_waitcnt lgkmcnt(0)
	v_add_f32_e32 v1, v1, v44
	ds_bpermute_b32 v44, v92, v1
	s_and_saveexec_b64 s[12:13], s[2:3]
	s_cbranch_execz .LBB0_412
	v_ashrrev_i32_e32 v49, 31, v48
	v_lshl_add_u64 v[46:47], v[48:49], 0, s[42:43]
	v_lshl_add_u64 v[46:47], v[46:47], 1, s[6:7]
	v_readfirstlane_b32 s60, v48
	s_nop 3
	v_readlane_b32 s61, v194, s60
	s_add_i32 s60, s60, 1
	s_nop 1
	v_mov_b32_e32 v45, s61
	v_readlane_b32 s61, v194, s60
	s_nop 1
	v_mov_b32_e32 v196, s61
	v_cndmask_b32_e64 v45, v45, v196, s[100:101]
	s_waitcnt lgkmcnt(0)
	v_add_f32_e32 v1, v1, v44
	v_fmac_f32_e32 v1, v84, v50
	v_lshlrev_b32_e32 v45, 16, v45
	v_mul_f32_e32 v46, 0xbfb8aa3b, v45
	v_exp_f32_e32 v46, v46
	s_nop 0
	v_add_f32_e32 v44, 1.0, v46
	v_div_scale_f32 v46, s[60:61], v44, v44, v45
	v_rcp_f32_e32 v47, v46
	v_div_scale_f32 v50, vcc, v45, v44, v45
	v_fma_f32 v51, -v46, v47, 1.0
	v_fmac_f32_e32 v47, v51, v47
	v_mul_f32_e32 v51, v50, v47
	v_fma_f32 v52, -v46, v51, v50
	v_fmac_f32_e32 v51, v52, v47
	v_fma_f32 v46, -v46, v51, v50
	v_div_fmas_f32 v46, v46, v47, v51
	v_div_fixup_f32 v44, v46, v44, v45
	v_mul_f32_e32 v1, v1, v44
	v_fmac_f32_e32 v93, v1, v1
	v_cvt_pk_bf16_f32 v1, v1, s0
	v_lshl_add_u64 v[44:45], v[48:49], 1, s[8:9]
	global_store_short v[44:45], v1, off
.LBB0_412:
	s_or_b64 exec, exec, s[12:13]
	s_waitcnt lgkmcnt(0)
	v_lshl_add_u32 v44, s40, 1, v85
	v_lshl_add_u32 v1, v44, 2, s87
	ds_read_b32 v46, v1
	v_mov_b32_e32 v1, v0
	s_waitcnt lgkmcnt(0)
	v_mul_f32_e32 v48, v75, v46
	v_pk_mul_f32 v[52:53], v[4:5], v[48:49] op_sel_hi:[1,0]
	v_pk_mul_f32 v[48:49], v[6:7], v[48:49] op_sel_hi:[1,0]
	s_waitcnt vmcnt(15)
	v_pk_fma_f32 v[50:51], v[0:1], v[42:43], v[48:49]
	v_pk_fma_f32 v[48:49], v[78:79], v[40:41], v[52:53]
	v_mul_f32_e32 v41, v11, v51
	v_mul_f32_e32 v40, v9, v49
	v_fmac_f32_e32 v40, v8, v48
	v_fmac_f32_e32 v41, v10, v50
	v_add_f32_e32 v40, v40, v41
	ds_bpermute_b32 v41, v88, v40
	v_lshlrev_b32_e32 v42, 7, v44
	v_ashrrev_i32_e32 v43, 31, v42
	v_lshl_add_u64 v[42:43], v[42:43], 2, v[80:81]
	global_store_dwordx4 v[42:43], v[48:51], off
	s_waitcnt lgkmcnt(0)
	v_add_f32_e32 v40, v40, v41
	ds_bpermute_b32 v41, v89, v40
	s_waitcnt lgkmcnt(0)
	v_add_f32_e32 v40, v40, v41
	ds_bpermute_b32 v41, v90, v40
	s_waitcnt lgkmcnt(0)
	v_add_f32_e32 v40, v40, v41
	ds_bpermute_b32 v41, v91, v40
	s_waitcnt lgkmcnt(0)
	v_add_f32_e32 v40, v40, v41
	ds_bpermute_b32 v41, v92, v40
	s_and_saveexec_b64 s[12:13], s[2:3]
	s_cbranch_execz .LBB0_414
	v_ashrrev_i32_e32 v45, 31, v44
	v_lshl_add_u64 v[42:43], v[44:45], 0, s[42:43]
	v_lshl_add_u64 v[42:43], v[42:43], 1, s[6:7]
	v_readfirstlane_b32 s40, v44
	s_nop 3
	v_readlane_b32 s41, v194, s40
	s_add_i32 s40, s40, 1
	s_nop 1
	v_mov_b32_e32 v42, s41
	v_readlane_b32 s41, v194, s40
	s_nop 1
	v_mov_b32_e32 v196, s41
	v_cndmask_b32_e64 v42, v42, v196, s[100:101]
	s_waitcnt lgkmcnt(0)
	v_add_f32_e32 v40, v40, v41
	v_fmac_f32_e32 v40, v84, v46
	v_lshlrev_b32_e32 v42, 16, v42
	v_mul_f32_e32 v43, 0xbfb8aa3b, v42
	v_exp_f32_e32 v43, v43
	s_nop 0
	v_add_f32_e32 v41, 1.0, v43
	v_div_scale_f32 v43, s[40:41], v41, v41, v42
	v_rcp_f32_e32 v47, v43
	v_div_scale_f32 v46, vcc, v42, v41, v42
	v_fma_f32 v48, -v43, v47, 1.0
	v_fmac_f32_e32 v47, v48, v47
	v_mul_f32_e32 v48, v46, v47
	v_fma_f32 v49, -v43, v48, v46
	v_fmac_f32_e32 v48, v49, v47
	v_fma_f32 v43, -v43, v48, v46
	v_div_fmas_f32 v43, v43, v47, v48
	v_div_fixup_f32 v41, v43, v41, v42
	v_mul_f32_e32 v40, v40, v41
	v_fmac_f32_e32 v93, v40, v40
	v_cvt_pk_bf16_f32 v42, v40, s0
	v_lshl_add_u64 v[40:41], v[44:45], 1, s[8:9]
	global_store_short v[40:41], v42, off
.LBB0_414:
	s_or_b64 exec, exec, s[12:13]
	v_lshl_add_u32 v40, s35, 1, v85
	s_waitcnt lgkmcnt(0)
	v_lshl_add_u32 v41, v40, 2, s87
	ds_read_b32 v42, v41
	s_waitcnt lgkmcnt(0)
	v_mul_f32_e32 v44, v75, v42
	v_pk_mul_f32 v[48:49], v[4:5], v[44:45] op_sel_hi:[1,0]
	v_pk_mul_f32 v[44:45], v[6:7], v[44:45] op_sel_hi:[1,0]
	s_waitcnt vmcnt(15)
	v_pk_fma_f32 v[46:47], v[0:1], v[38:39], v[44:45]
	v_pk_fma_f32 v[44:45], v[78:79], v[36:37], v[48:49]
	v_mul_f32_e32 v36, v11, v47
	v_mul_f32_e32 v1, v9, v45
	v_fmac_f32_e32 v1, v8, v44
	v_fmac_f32_e32 v36, v10, v46
	v_add_f32_e32 v1, v1, v36
	ds_bpermute_b32 v36, v88, v1
	v_lshlrev_b32_e32 v38, 7, v40
	v_ashrrev_i32_e32 v39, 31, v38
	v_lshl_add_u64 v[38:39], v[38:39], 2, v[80:81]
	global_store_dwordx4 v[38:39], v[44:47], off
	s_waitcnt lgkmcnt(0)
	v_add_f32_e32 v1, v1, v36
	ds_bpermute_b32 v36, v89, v1
	s_waitcnt lgkmcnt(0)
	v_add_f32_e32 v1, v1, v36
	ds_bpermute_b32 v36, v90, v1
	s_waitcnt lgkmcnt(0)
	v_add_f32_e32 v1, v1, v36
	ds_bpermute_b32 v36, v91, v1
	s_waitcnt lgkmcnt(0)
	v_add_f32_e32 v1, v1, v36
	ds_bpermute_b32 v36, v92, v1
	s_and_saveexec_b64 s[12:13], s[2:3]
	s_cbranch_execz .LBB0_416
	v_ashrrev_i32_e32 v41, 31, v40
	v_lshl_add_u64 v[38:39], v[40:41], 0, s[42:43]
	v_lshl_add_u64 v[38:39], v[38:39], 1, s[6:7]
	v_readfirstlane_b32 s40, v40
	s_nop 3
	v_readlane_b32 s41, v194, s40
	s_add_i32 s40, s40, 1
	s_nop 1
	v_mov_b32_e32 v37, s41
	v_readlane_b32 s41, v194, s40
	s_nop 1
	v_mov_b32_e32 v196, s41
	v_cndmask_b32_e64 v37, v37, v196, s[100:101]
	s_waitcnt lgkmcnt(0)
	v_add_f32_e32 v1, v1, v36
	v_fmac_f32_e32 v1, v84, v42
	v_lshlrev_b32_e32 v37, 16, v37
	v_mul_f32_e32 v38, 0xbfb8aa3b, v37
	v_exp_f32_e32 v38, v38
	s_nop 0
	v_add_f32_e32 v36, 1.0, v38
	v_div_scale_f32 v38, s[40:41], v36, v36, v37
	v_rcp_f32_e32 v39, v38
	v_div_scale_f32 v42, vcc, v37, v36, v37
	v_fma_f32 v43, -v38, v39, 1.0
	v_fmac_f32_e32 v39, v43, v39
	v_mul_f32_e32 v43, v42, v39
	v_fma_f32 v44, -v38, v43, v42
	v_fmac_f32_e32 v43, v44, v39
	v_fma_f32 v38, -v38, v43, v42
	v_div_fmas_f32 v38, v38, v39, v43
	v_div_fixup_f32 v36, v38, v36, v37
	v_mul_f32_e32 v1, v1, v36
	v_fmac_f32_e32 v93, v1, v1
	v_cvt_pk_bf16_f32 v1, v1, s0
	v_lshl_add_u64 v[36:37], v[40:41], 1, s[8:9]
	global_store_short v[36:37], v1, off
.LBB0_416:
	s_or_b64 exec, exec, s[12:13]
	s_waitcnt lgkmcnt(0)
	v_lshl_add_u32 v36, s34, 1, v85
	v_lshl_add_u32 v1, v36, 2, s87
	ds_read_b32 v38, v1
	v_mov_b32_e32 v1, v0
	s_waitcnt lgkmcnt(0)
	v_mul_f32_e32 v40, v75, v38
	v_pk_mul_f32 v[44:45], v[4:5], v[40:41] op_sel_hi:[1,0]
	v_pk_mul_f32 v[40:41], v[6:7], v[40:41] op_sel_hi:[1,0]
	s_waitcnt vmcnt(15)
	v_pk_fma_f32 v[42:43], v[0:1], v[34:35], v[40:41]
	v_pk_fma_f32 v[40:41], v[78:79], v[32:33], v[44:45]
	v_mul_f32_e32 v33, v11, v43
	v_mul_f32_e32 v32, v9, v41
	v_fmac_f32_e32 v32, v8, v40
	v_fmac_f32_e32 v33, v10, v42
	v_add_f32_e32 v32, v32, v33
	ds_bpermute_b32 v33, v88, v32
	v_lshlrev_b32_e32 v34, 7, v36
	v_ashrrev_i32_e32 v35, 31, v34
	v_lshl_add_u64 v[34:35], v[34:35], 2, v[80:81]
	global_store_dwordx4 v[34:35], v[40:43], off
	s_waitcnt lgkmcnt(0)
	v_add_f32_e32 v32, v32, v33
	ds_bpermute_b32 v33, v89, v32
	s_waitcnt lgkmcnt(0)
	v_add_f32_e32 v32, v32, v33
	ds_bpermute_b32 v33, v90, v32
	s_waitcnt lgkmcnt(0)
	v_add_f32_e32 v32, v32, v33
	ds_bpermute_b32 v33, v91, v32
	s_waitcnt lgkmcnt(0)
	v_add_f32_e32 v32, v32, v33
	ds_bpermute_b32 v33, v92, v32
	s_and_saveexec_b64 s[12:13], s[2:3]
	s_cbranch_execz .LBB0_418
	v_ashrrev_i32_e32 v37, 31, v36
	v_lshl_add_u64 v[34:35], v[36:37], 0, s[42:43]
	v_lshl_add_u64 v[34:35], v[34:35], 1, s[6:7]
	v_readfirstlane_b32 s34, v36
	s_nop 3
	v_readlane_b32 s35, v194, s34
	s_add_i32 s34, s34, 1
	s_nop 1
	v_mov_b32_e32 v34, s35
	v_readlane_b32 s35, v194, s34
	s_nop 1
	v_mov_b32_e32 v196, s35
	v_cndmask_b32_e64 v34, v34, v196, s[100:101]
	s_waitcnt lgkmcnt(0)
	v_add_f32_e32 v32, v32, v33
	v_fmac_f32_e32 v32, v84, v38
	v_lshlrev_b32_e32 v34, 16, v34
	v_mul_f32_e32 v35, 0xbfb8aa3b, v34
	v_exp_f32_e32 v35, v35
	s_nop 0
	v_add_f32_e32 v33, 1.0, v35
	v_div_scale_f32 v35, s[34:35], v33, v33, v34
	v_rcp_f32_e32 v39, v35
	v_div_scale_f32 v38, vcc, v34, v33, v34
	v_fma_f32 v40, -v35, v39, 1.0
	v_fmac_f32_e32 v39, v40, v39
	v_mul_f32_e32 v40, v38, v39
	v_fma_f32 v41, -v35, v40, v38
	v_fmac_f32_e32 v40, v41, v39
	v_fma_f32 v35, -v35, v40, v38
	v_div_fmas_f32 v35, v35, v39, v40
	v_div_fixup_f32 v33, v35, v33, v34
	v_mul_f32_e32 v32, v32, v33
	v_fmac_f32_e32 v93, v32, v32
	v_cvt_pk_bf16_f32 v34, v32, s0
	v_lshl_add_u64 v[32:33], v[36:37], 1, s[8:9]
	global_store_short v[32:33], v34, off
.LBB0_418:
	s_or_b64 exec, exec, s[12:13]
	v_lshl_add_u32 v32, s31, 1, v85
	s_waitcnt lgkmcnt(0)
	v_lshl_add_u32 v33, v32, 2, s87
	ds_read_b32 v34, v33
	s_waitcnt lgkmcnt(0)
	v_mul_f32_e32 v36, v75, v34
	v_pk_mul_f32 v[40:41], v[4:5], v[36:37] op_sel_hi:[1,0]
	v_pk_mul_f32 v[36:37], v[6:7], v[36:37] op_sel_hi:[1,0]
	s_waitcnt vmcnt(15)
	v_pk_fma_f32 v[38:39], v[0:1], v[30:31], v[36:37]
	v_pk_fma_f32 v[36:37], v[78:79], v[28:29], v[40:41]
	v_mul_f32_e32 v28, v11, v39
	v_mul_f32_e32 v1, v9, v37
	v_fmac_f32_e32 v1, v8, v36
	v_fmac_f32_e32 v28, v10, v38
	v_add_f32_e32 v1, v1, v28
	ds_bpermute_b32 v28, v88, v1
	v_lshlrev_b32_e32 v30, 7, v32
	v_ashrrev_i32_e32 v31, 31, v30
	v_lshl_add_u64 v[30:31], v[30:31], 2, v[80:81]
	global_store_dwordx4 v[30:31], v[36:39], off
	s_waitcnt lgkmcnt(0)
	v_add_f32_e32 v1, v1, v28
	ds_bpermute_b32 v28, v89, v1
	s_waitcnt lgkmcnt(0)
	v_add_f32_e32 v1, v1, v28
	ds_bpermute_b32 v28, v90, v1
	s_waitcnt lgkmcnt(0)
	v_add_f32_e32 v1, v1, v28
	ds_bpermute_b32 v28, v91, v1
	s_waitcnt lgkmcnt(0)
	v_add_f32_e32 v1, v1, v28
	ds_bpermute_b32 v28, v92, v1
	s_and_saveexec_b64 s[12:13], s[2:3]
	s_cbranch_execz .LBB0_420
	v_ashrrev_i32_e32 v33, 31, v32
	v_lshl_add_u64 v[30:31], v[32:33], 0, s[42:43]
	v_lshl_add_u64 v[30:31], v[30:31], 1, s[6:7]
	v_readfirstlane_b32 s34, v32
	s_nop 3
	v_readlane_b32 s35, v194, s34
	s_add_i32 s34, s34, 1
	s_nop 1
	v_mov_b32_e32 v29, s35
	v_readlane_b32 s35, v194, s34
	s_nop 1
	v_mov_b32_e32 v196, s35
	v_cndmask_b32_e64 v29, v29, v196, s[100:101]
	s_waitcnt lgkmcnt(0)
	v_add_f32_e32 v1, v1, v28
	v_fmac_f32_e32 v1, v84, v34
	v_lshlrev_b32_e32 v29, 16, v29
	v_mul_f32_e32 v30, 0xbfb8aa3b, v29
	v_exp_f32_e32 v30, v30
	s_nop 0
	v_add_f32_e32 v28, 1.0, v30
	v_div_scale_f32 v30, s[34:35], v28, v28, v29
	v_rcp_f32_e32 v31, v30
	v_div_scale_f32 v34, vcc, v29, v28, v29
	v_fma_f32 v35, -v30, v31, 1.0
	v_fmac_f32_e32 v31, v35, v31
	v_mul_f32_e32 v35, v34, v31
	v_fma_f32 v36, -v30, v35, v34
	v_fmac_f32_e32 v35, v36, v31
	v_fma_f32 v30, -v30, v35, v34
	v_div_fmas_f32 v30, v30, v31, v35
	v_div_fixup_f32 v28, v30, v28, v29
	v_mul_f32_e32 v1, v1, v28
	v_fmac_f32_e32 v93, v1, v1
	v_cvt_pk_bf16_f32 v1, v1, s0
	v_lshl_add_u64 v[28:29], v[32:33], 1, s[8:9]
	global_store_short v[28:29], v1, off
.LBB0_420:
	s_or_b64 exec, exec, s[12:13]
	s_waitcnt lgkmcnt(0)
	v_lshl_add_u32 v28, s30, 1, v85
	v_lshl_add_u32 v1, v28, 2, s87
	ds_read_b32 v30, v1
	v_mov_b32_e32 v1, v0
	s_waitcnt lgkmcnt(0)
	v_mul_f32_e32 v32, v75, v30
	v_pk_mul_f32 v[36:37], v[4:5], v[32:33] op_sel_hi:[1,0]
	v_pk_mul_f32 v[32:33], v[6:7], v[32:33] op_sel_hi:[1,0]
	s_waitcnt vmcnt(15)
	v_pk_fma_f32 v[34:35], v[0:1], v[26:27], v[32:33]
	v_pk_fma_f32 v[32:33], v[78:79], v[24:25], v[36:37]
	v_mul_f32_e32 v25, v11, v35
	v_mul_f32_e32 v24, v9, v33
	v_fmac_f32_e32 v24, v8, v32
	v_fmac_f32_e32 v25, v10, v34
	v_add_f32_e32 v24, v24, v25
	ds_bpermute_b32 v25, v88, v24
	v_lshlrev_b32_e32 v26, 7, v28
	v_ashrrev_i32_e32 v27, 31, v26
	v_lshl_add_u64 v[26:27], v[26:27], 2, v[80:81]
	global_store_dwordx4 v[26:27], v[32:35], off
	s_waitcnt lgkmcnt(0)
	v_add_f32_e32 v24, v24, v25
	ds_bpermute_b32 v25, v89, v24
	s_waitcnt lgkmcnt(0)
	v_add_f32_e32 v24, v24, v25
	ds_bpermute_b32 v25, v90, v24
	s_waitcnt lgkmcnt(0)
	v_add_f32_e32 v24, v24, v25
	ds_bpermute_b32 v25, v91, v24
	s_waitcnt lgkmcnt(0)
	v_add_f32_e32 v24, v24, v25
	ds_bpermute_b32 v25, v92, v24
	s_and_saveexec_b64 s[12:13], s[2:3]
	s_cbranch_execz .LBB0_422
	v_ashrrev_i32_e32 v29, 31, v28
	v_lshl_add_u64 v[26:27], v[28:29], 0, s[42:43]
	v_lshl_add_u64 v[26:27], v[26:27], 1, s[6:7]
	v_readfirstlane_b32 s30, v28
	s_nop 3
	v_readlane_b32 s31, v194, s30
	s_add_i32 s30, s30, 1
	s_nop 1
	v_mov_b32_e32 v26, s31
	v_readlane_b32 s31, v194, s30
	s_nop 1
	v_mov_b32_e32 v196, s31
	v_cndmask_b32_e64 v26, v26, v196, s[100:101]
	s_waitcnt lgkmcnt(0)
	v_add_f32_e32 v24, v24, v25
	v_fmac_f32_e32 v24, v84, v30
	v_lshlrev_b32_e32 v26, 16, v26
	v_mul_f32_e32 v27, 0xbfb8aa3b, v26
	v_exp_f32_e32 v27, v27
	s_nop 0
	v_add_f32_e32 v25, 1.0, v27
	v_div_scale_f32 v27, s[30:31], v25, v25, v26
	v_rcp_f32_e32 v31, v27
	v_div_scale_f32 v30, vcc, v26, v25, v26
	v_fma_f32 v32, -v27, v31, 1.0
	v_fmac_f32_e32 v31, v32, v31
	v_mul_f32_e32 v32, v30, v31
	v_fma_f32 v33, -v27, v32, v30
	v_fmac_f32_e32 v32, v33, v31
	v_fma_f32 v27, -v27, v32, v30
	v_div_fmas_f32 v27, v27, v31, v32
	v_div_fixup_f32 v25, v27, v25, v26
	v_mul_f32_e32 v24, v24, v25
	v_fmac_f32_e32 v93, v24, v24
	v_cvt_pk_bf16_f32 v26, v24, s0
	v_lshl_add_u64 v[24:25], v[28:29], 1, s[8:9]
	global_store_short v[24:25], v26, off
.LBB0_422:
	s_or_b64 exec, exec, s[12:13]
	v_lshl_add_u32 v24, s15, 1, v85
	s_waitcnt lgkmcnt(0)
	v_lshl_add_u32 v25, v24, 2, s87
	ds_read_b32 v26, v25
	s_waitcnt lgkmcnt(0)
	v_mul_f32_e32 v28, v75, v26
	v_pk_mul_f32 v[32:33], v[4:5], v[28:29] op_sel_hi:[1,0]
	v_pk_mul_f32 v[28:29], v[6:7], v[28:29] op_sel_hi:[1,0]
	s_waitcnt vmcnt(15)
	v_pk_fma_f32 v[30:31], v[0:1], v[22:23], v[28:29]
	v_pk_fma_f32 v[28:29], v[78:79], v[20:21], v[32:33]
	v_mul_f32_e32 v20, v11, v31
	v_mul_f32_e32 v1, v9, v29
	v_fmac_f32_e32 v1, v8, v28
	v_fmac_f32_e32 v20, v10, v30
	v_add_f32_e32 v1, v1, v20
	ds_bpermute_b32 v20, v88, v1
	v_lshlrev_b32_e32 v22, 7, v24
	v_ashrrev_i32_e32 v23, 31, v22
	v_lshl_add_u64 v[22:23], v[22:23], 2, v[80:81]
	global_store_dwordx4 v[22:23], v[28:31], off
	s_waitcnt lgkmcnt(0)
	v_add_f32_e32 v1, v1, v20
	ds_bpermute_b32 v20, v89, v1
	s_waitcnt lgkmcnt(0)
	v_add_f32_e32 v1, v1, v20
	ds_bpermute_b32 v20, v90, v1
	s_waitcnt lgkmcnt(0)
	v_add_f32_e32 v1, v1, v20
	ds_bpermute_b32 v20, v91, v1
	s_waitcnt lgkmcnt(0)
	v_add_f32_e32 v1, v1, v20
	ds_bpermute_b32 v20, v92, v1
	s_and_saveexec_b64 s[12:13], s[2:3]
	s_cbranch_execz .LBB0_424
	v_ashrrev_i32_e32 v25, 31, v24
	v_lshl_add_u64 v[22:23], v[24:25], 0, s[42:43]
	v_lshl_add_u64 v[22:23], v[22:23], 1, s[6:7]
	v_readfirstlane_b32 s30, v24
	s_nop 3
	v_readlane_b32 s31, v194, s30
	s_add_i32 s30, s30, 1
	s_nop 1
	v_mov_b32_e32 v21, s31
	v_readlane_b32 s31, v194, s30
	s_nop 1
	v_mov_b32_e32 v196, s31
	v_cndmask_b32_e64 v21, v21, v196, s[100:101]
	s_waitcnt lgkmcnt(0)
	v_add_f32_e32 v1, v1, v20
	v_fmac_f32_e32 v1, v84, v26
	v_lshlrev_b32_e32 v21, 16, v21
	v_mul_f32_e32 v22, 0xbfb8aa3b, v21
	v_exp_f32_e32 v22, v22
	s_nop 0
	v_add_f32_e32 v20, 1.0, v22
	v_div_scale_f32 v22, s[30:31], v20, v20, v21
	v_rcp_f32_e32 v23, v22
	v_div_scale_f32 v26, vcc, v21, v20, v21
	v_fma_f32 v27, -v22, v23, 1.0
	v_fmac_f32_e32 v23, v27, v23
	v_mul_f32_e32 v27, v26, v23
	v_fma_f32 v28, -v22, v27, v26
	v_fmac_f32_e32 v27, v28, v23
	v_fma_f32 v22, -v22, v27, v26
	v_div_fmas_f32 v22, v22, v23, v27
	v_div_fixup_f32 v20, v22, v20, v21
	v_mul_f32_e32 v1, v1, v20
	v_fmac_f32_e32 v93, v1, v1
	v_cvt_pk_bf16_f32 v1, v1, s0
	v_lshl_add_u64 v[20:21], v[24:25], 1, s[8:9]
	global_store_short v[20:21], v1, off
.LBB0_424:
	s_or_b64 exec, exec, s[12:13]
	s_waitcnt lgkmcnt(0)
	v_lshl_add_u32 v20, s14, 1, v85
	v_lshl_add_u32 v1, v20, 2, s87
	ds_read_b32 v22, v1
	v_mov_b32_e32 v1, v0
	s_waitcnt lgkmcnt(0)
	v_mul_f32_e32 v24, v75, v22
	v_pk_mul_f32 v[28:29], v[4:5], v[24:25] op_sel_hi:[1,0]
	v_pk_mul_f32 v[24:25], v[6:7], v[24:25] op_sel_hi:[1,0]
	s_waitcnt vmcnt(15)
	v_pk_fma_f32 v[26:27], v[0:1], v[18:19], v[24:25]
	v_pk_fma_f32 v[24:25], v[78:79], v[16:17], v[28:29]
	v_mul_f32_e32 v17, v11, v27
	v_mul_f32_e32 v16, v9, v25
	v_fmac_f32_e32 v16, v8, v24
	v_fmac_f32_e32 v17, v10, v26
	v_add_f32_e32 v16, v16, v17
	ds_bpermute_b32 v17, v88, v16
	v_lshlrev_b32_e32 v18, 7, v20
	v_ashrrev_i32_e32 v19, 31, v18
	v_lshl_add_u64 v[18:19], v[18:19], 2, v[80:81]
	global_store_dwordx4 v[18:19], v[24:27], off
	s_waitcnt lgkmcnt(0)
	v_add_f32_e32 v16, v16, v17
	ds_bpermute_b32 v17, v89, v16
	s_waitcnt lgkmcnt(0)
	v_add_f32_e32 v16, v16, v17
	ds_bpermute_b32 v17, v90, v16
	s_waitcnt lgkmcnt(0)
	v_add_f32_e32 v16, v16, v17
	ds_bpermute_b32 v17, v91, v16
	s_waitcnt lgkmcnt(0)
	v_add_f32_e32 v16, v16, v17
	ds_bpermute_b32 v17, v92, v16
	s_and_saveexec_b64 s[12:13], s[2:3]
	s_cbranch_execz .LBB0_426
	v_ashrrev_i32_e32 v21, 31, v20
	v_lshl_add_u64 v[18:19], v[20:21], 0, s[42:43]
	v_lshl_add_u64 v[18:19], v[18:19], 1, s[6:7]
	v_readfirstlane_b32 s14, v20
	s_nop 3
	v_readlane_b32 s15, v194, s14
	s_add_i32 s14, s14, 1
	s_nop 1
	v_mov_b32_e32 v18, s15
	v_readlane_b32 s15, v194, s14
	s_nop 1
	v_mov_b32_e32 v196, s15
	v_cndmask_b32_e64 v18, v18, v196, s[100:101]
	s_waitcnt lgkmcnt(0)
	v_add_f32_e32 v16, v16, v17
	v_fmac_f32_e32 v16, v84, v22
	v_lshlrev_b32_e32 v18, 16, v18
	v_mul_f32_e32 v19, 0xbfb8aa3b, v18
	v_exp_f32_e32 v19, v19
	s_nop 0
	v_add_f32_e32 v17, 1.0, v19
	v_div_scale_f32 v19, s[14:15], v17, v17, v18
	v_rcp_f32_e32 v23, v19
	v_div_scale_f32 v22, vcc, v18, v17, v18
	v_fma_f32 v24, -v19, v23, 1.0
	v_fmac_f32_e32 v23, v24, v23
	v_mul_f32_e32 v24, v22, v23
	v_fma_f32 v25, -v19, v24, v22
	v_fmac_f32_e32 v24, v25, v23
	v_fma_f32 v19, -v19, v24, v22
	v_div_fmas_f32 v19, v19, v23, v24
	v_div_fixup_f32 v17, v19, v17, v18
	v_mul_f32_e32 v16, v16, v17
	v_fmac_f32_e32 v93, v16, v16
	v_cvt_pk_bf16_f32 v18, v16, s0
	v_lshl_add_u64 v[16:17], v[20:21], 1, s[8:9]
	global_store_short v[16:17], v18, off
.LBB0_426:
	s_or_b64 exec, exec, s[12:13]
	v_lshl_add_u32 v16, s1, 1, v85
	s_waitcnt lgkmcnt(0)
	v_lshl_add_u32 v17, v16, 2, s87
	ds_read_b32 v18, v17
	s_waitcnt lgkmcnt(0)
	v_mul_f32_e32 v20, v75, v18
	v_pk_mul_f32 v[24:25], v[4:5], v[20:21] op_sel_hi:[1,0]
	v_pk_mul_f32 v[20:21], v[6:7], v[20:21] op_sel_hi:[1,0]
	s_waitcnt vmcnt(15)
	v_pk_fma_f32 v[22:23], v[0:1], v[14:15], v[20:21]
	v_pk_fma_f32 v[20:21], v[78:79], v[12:13], v[24:25]
	v_mul_f32_e32 v12, v11, v23
	v_mul_f32_e32 v1, v9, v21
	v_fmac_f32_e32 v1, v8, v20
	v_fmac_f32_e32 v12, v10, v22
	v_add_f32_e32 v1, v1, v12
	ds_bpermute_b32 v12, v88, v1
	v_lshlrev_b32_e32 v14, 7, v16
	v_ashrrev_i32_e32 v15, 31, v14
	v_lshl_add_u64 v[14:15], v[14:15], 2, v[80:81]
	global_store_dwordx4 v[14:15], v[20:23], off
	s_waitcnt lgkmcnt(0)
	v_add_f32_e32 v1, v1, v12
	ds_bpermute_b32 v12, v89, v1
	s_waitcnt lgkmcnt(0)
	v_add_f32_e32 v1, v1, v12
	ds_bpermute_b32 v12, v90, v1
	s_waitcnt lgkmcnt(0)
	v_add_f32_e32 v1, v1, v12
	ds_bpermute_b32 v12, v91, v1
	s_waitcnt lgkmcnt(0)
	v_add_f32_e32 v1, v1, v12
	ds_bpermute_b32 v12, v92, v1
	s_and_saveexec_b64 s[12:13], s[2:3]
	s_cbranch_execz .LBB0_395
	v_ashrrev_i32_e32 v17, 31, v16
	v_lshl_add_u64 v[14:15], v[16:17], 0, s[42:43]
	v_lshl_add_u64 v[14:15], v[14:15], 1, s[6:7]
	v_readfirstlane_b32 s14, v16
	s_nop 3
	v_readlane_b32 s15, v194, s14
	s_add_i32 s14, s14, 1
	s_nop 1
	v_mov_b32_e32 v13, s15
	v_readlane_b32 s15, v194, s14
	s_nop 1
	v_mov_b32_e32 v196, s15
	v_cndmask_b32_e64 v13, v13, v196, s[100:101]
	s_waitcnt lgkmcnt(0)
	v_add_f32_e32 v1, v1, v12
	v_fmac_f32_e32 v1, v84, v18
	v_lshlrev_b32_e32 v13, 16, v13
	v_mul_f32_e32 v14, 0xbfb8aa3b, v13
	v_exp_f32_e32 v14, v14
	s_nop 0
	v_add_f32_e32 v12, 1.0, v14
	v_div_scale_f32 v14, s[14:15], v12, v12, v13
	v_rcp_f32_e32 v15, v14
	v_div_scale_f32 v18, vcc, v13, v12, v13
	v_fma_f32 v19, -v14, v15, 1.0
	v_fmac_f32_e32 v15, v19, v15
	v_mul_f32_e32 v19, v18, v15
	v_fma_f32 v20, -v14, v19, v18
	v_fmac_f32_e32 v19, v20, v15
	v_fma_f32 v14, -v14, v19, v18
	v_div_fmas_f32 v14, v14, v15, v19
	v_div_fixup_f32 v12, v14, v12, v13
	v_mul_f32_e32 v1, v1, v12
	v_fmac_f32_e32 v93, v1, v1
	v_cvt_pk_bf16_f32 v1, v1, s0
	v_lshl_add_u64 v[12:13], v[16:17], 1, s[8:9]
	global_store_short v[12:13], v1, off
	s_branch .LBB0_395

.LBB0_628:
	v_lshl_or_b32 v2, s59, 8, v153
	s_mov_b64 s[0:1], exec
	v_readlane_b32 s56, v237, 12
	v_readlane_b32 s57, v237, 13
	v_readlane_b32 s58, v237, 14
	v_readlane_b32 s59, v237, 15
	v_readlane_b32 s60, v237, 16
	v_readlane_b32 s61, v237, 17
	v_readlane_b32 s62, v237, 18
	v_readlane_b32 s63, v237, 19
	v_readlane_b32 s64, v237, 20
	v_readlane_b32 s65, v237, 21
	v_readlane_b32 s66, v237, 22
	v_readlane_b32 s67, v237, 23
	v_readlane_b32 s68, v237, 24
	v_readlane_b32 s69, v237, 25
	v_readlane_b32 s70, v237, 26
	v_readlane_b32 s71, v237, 27
	v_lshlrev_b32_e32 v3, 2, v2
	v_lshl_add_u32 v3, v144, 13, v3
	v_lshlrev_b32_e32 v1, 1, v2
	v_lshl_add_u32 v1, v144, 12, v1
	v_xor_b32_e32 v146, 16, v150
	v_lshlrev_b32_e32 v146, 2, v146
	v_xor_b32_e32 v147, 32, v150
	v_lshlrev_b32_e32 v147, 2, v147
	global_load_dwordx4 v[156:159], v3, s[56:57]
	global_load_dwordx4 v[160:163], v3, s[56:57] offset:64
	global_load_dwordx4 v[164:167], v3, s[56:57] offset:512
	global_load_dwordx4 v[168:171], v3, s[56:57] offset:576
	v_add_u32_e32 v230, 0x20000, v3
	global_load_dwordx4 v[174:177], v230, s[56:57]
	global_load_dwordx4 v[178:181], v230, s[56:57] offset:64
	global_load_dwordx4 v[182:185], v230, s[56:57] offset:512
	global_load_dwordx4 v[186:189], v230, s[56:57] offset:576
	v_add_u32_e32 v230, 0x40000, v3
	global_load_dwordx4 v[190:193], v230, s[56:57]
	global_load_dwordx4 v[194:197], v230, s[56:57] offset:64
	global_load_dwordx4 v[198:201], v230, s[56:57] offset:512
	global_load_dwordx4 v[202:205], v230, s[56:57] offset:576
	v_add_u32_e32 v230, 0x60000, v3
	global_load_dwordx4 v[206:209], v230, s[56:57]
	global_load_dwordx4 v[210:213], v230, s[56:57] offset:64
	global_load_dwordx4 v[214:217], v230, s[56:57] offset:512
	global_load_dwordx4 v[218:221], v230, s[56:57] offset:576
	s_waitcnt vmcnt(12)
	v_pk_add_f32 v[130:131], v[130:131], v[158:159]
	v_pk_add_f32 v[128:129], v[128:129], v[156:157]
	v_cvt_pk_bf16_f32 v222, v128, v129
	v_cvt_pk_bf16_f32 v223, v130, v131
	v_mul_f32_e32 v224, v129, v129
	v_mul_f32_e32 v225, v131, v131
	v_fmac_f32_e32 v224, v128, v128
	v_fmac_f32_e32 v225, v130, v130
	global_store_dwordx2 v1, v[222:223], s[20:21]
	v_add_f32_e32 v226, v224, v225
	v_pk_add_f32 v[126:127], v[126:127], v[162:163]
	v_pk_add_f32 v[124:125], v[124:125], v[160:161]
	v_cvt_pk_bf16_f32 v222, v124, v125
	v_cvt_pk_bf16_f32 v223, v126, v127
	v_mul_f32_e32 v224, v125, v125
	v_mul_f32_e32 v225, v127, v127
	v_fmac_f32_e32 v224, v124, v124
	v_fmac_f32_e32 v225, v126, v126
	global_store_dwordx2 v1, v[222:223], s[20:21] offset:32
	v_add_f32_e32 v227, v224, v225
	v_pk_add_f32 v[122:123], v[122:123], v[166:167]
	v_pk_add_f32 v[120:121], v[120:121], v[164:165]
	v_cvt_pk_bf16_f32 v222, v120, v121
	v_cvt_pk_bf16_f32 v223, v122, v123
	v_mul_f32_e32 v224, v121, v121
	v_mul_f32_e32 v225, v123, v123
	v_fmac_f32_e32 v224, v120, v120
	v_fmac_f32_e32 v225, v122, v122
	global_store_dwordx2 v1, v[222:223], s[20:21] offset:256
	v_add_f32_e32 v228, v224, v225
	v_pk_add_f32 v[118:119], v[118:119], v[170:171]
	v_pk_add_f32 v[116:117], v[116:117], v[168:169]
	v_cvt_pk_bf16_f32 v222, v116, v117
	v_cvt_pk_bf16_f32 v223, v118, v119
	v_mul_f32_e32 v224, v117, v117
	v_mul_f32_e32 v225, v119, v119
	v_fmac_f32_e32 v224, v116, v116
	v_fmac_f32_e32 v225, v118, v118
	global_store_dwordx2 v1, v[222:223], s[20:21] offset:288
	v_add_f32_e32 v229, v224, v225
	v_add_f32_e32 v226, v226, v227
	v_add_f32_e32 v226, v226, v228
	v_add_f32_e32 v226, v226, v229
	ds_bpermute_b32 v224, v146, v226
	v_lshlrev_b32_e32 v225, 2, v144
	s_waitcnt lgkmcnt(0)
	v_add_f32_e32 v226, v226, v224
	ds_bpermute_b32 v224, v147, v226
	s_waitcnt lgkmcnt(0)
	v_add_f32_e32 v226, v226, v224
	s_and_b64 exec, exec, s[2:3]
	global_atomic_add_f32 v225, v226, s[22:23]
	s_mov_b64 exec, s[0:1]
	v_add_u32_e32 v230, 0x100000, v3
	global_load_dwordx4 v[156:159], v230, s[56:57]
	global_load_dwordx4 v[160:163], v230, s[56:57] offset:64
	global_load_dwordx4 v[164:167], v230, s[56:57] offset:512
	global_load_dwordx4 v[168:171], v230, s[56:57] offset:576
	s_waitcnt vmcnt(16)
	v_add_u32_e32 v231, 0x10000, v1
	v_pk_add_f32 v[114:115], v[114:115], v[176:177]
	v_pk_add_f32 v[112:113], v[112:113], v[174:175]
	v_cvt_pk_bf16_f32 v222, v112, v113
	v_cvt_pk_bf16_f32 v223, v114, v115
	v_mul_f32_e32 v224, v113, v113
	v_mul_f32_e32 v225, v115, v115
	v_fmac_f32_e32 v224, v112, v112
	v_fmac_f32_e32 v225, v114, v114
	global_store_dwordx2 v231, v[222:223], s[20:21]
	v_add_f32_e32 v226, v224, v225
	v_pk_add_f32 v[110:111], v[110:111], v[180:181]
	v_pk_add_f32 v[108:109], v[108:109], v[178:179]
	v_cvt_pk_bf16_f32 v222, v108, v109
	v_cvt_pk_bf16_f32 v223, v110, v111
	v_mul_f32_e32 v224, v109, v109
	v_mul_f32_e32 v225, v111, v111
	v_fmac_f32_e32 v224, v108, v108
	v_fmac_f32_e32 v225, v110, v110
	global_store_dwordx2 v231, v[222:223], s[20:21] offset:32
	v_add_f32_e32 v227, v224, v225
	v_pk_add_f32 v[106:107], v[106:107], v[184:185]
	v_pk_add_f32 v[104:105], v[104:105], v[182:183]
	v_cvt_pk_bf16_f32 v222, v104, v105
	v_cvt_pk_bf16_f32 v223, v106, v107
	v_mul_f32_e32 v224, v105, v105
	v_mul_f32_e32 v225, v107, v107
	v_fmac_f32_e32 v224, v104, v104
	v_fmac_f32_e32 v225, v106, v106
	global_store_dwordx2 v231, v[222:223], s[20:21] offset:256
	v_add_f32_e32 v228, v224, v225
	v_pk_add_f32 v[102:103], v[102:103], v[188:189]
	v_pk_add_f32 v[100:101], v[100:101], v[186:187]
	v_cvt_pk_bf16_f32 v222, v100, v101
	v_cvt_pk_bf16_f32 v223, v102, v103
	v_mul_f32_e32 v224, v101, v101
	v_mul_f32_e32 v225, v103, v103
	v_fmac_f32_e32 v224, v100, v100
	v_fmac_f32_e32 v225, v102, v102
	global_store_dwordx2 v231, v[222:223], s[20:21] offset:288
	v_add_f32_e32 v229, v224, v225
	v_add_f32_e32 v226, v226, v227
	v_add_f32_e32 v226, v226, v228
	v_add_f32_e32 v226, v226, v229
	ds_bpermute_b32 v224, v146, v226
	v_add_u32_e32 v225, 0x10, v144
	v_lshlrev_b32_e32 v225, 2, v225
	s_waitcnt lgkmcnt(0)
	v_add_f32_e32 v226, v226, v224
	ds_bpermute_b32 v224, v147, v226
	s_waitcnt lgkmcnt(0)
	v_add_f32_e32 v226, v226, v224
	s_and_b64 exec, exec, s[2:3]
	global_atomic_add_f32 v225, v226, s[22:23]
	s_mov_b64 exec, s[0:1]
	v_add_u32_e32 v230, 0x120000, v3
	global_load_dwordx4 v[174:177], v230, s[56:57]
	global_load_dwordx4 v[178:181], v230, s[56:57] offset:64
	global_load_dwordx4 v[182:185], v230, s[56:57] offset:512
	global_load_dwordx4 v[186:189], v230, s[56:57] offset:576
	s_waitcnt vmcnt(20)
	v_add_u32_e32 v231, 0x20000, v1
	v_pk_add_f32 v[98:99], v[98:99], v[192:193]
	v_pk_add_f32 v[96:97], v[96:97], v[190:191]
	v_cvt_pk_bf16_f32 v222, v96, v97
	v_cvt_pk_bf16_f32 v223, v98, v99
	v_mul_f32_e32 v224, v97, v97
	v_mul_f32_e32 v225, v99, v99
	v_fmac_f32_e32 v224, v96, v96
	v_fmac_f32_e32 v225, v98, v98
	global_store_dwordx2 v231, v[222:223], s[20:21]
	v_add_f32_e32 v226, v224, v225
	v_pk_add_f32 v[94:95], v[94:95], v[196:197]
	v_pk_add_f32 v[92:93], v[92:93], v[194:195]
	v_cvt_pk_bf16_f32 v222, v92, v93
	v_cvt_pk_bf16_f32 v223, v94, v95
	v_mul_f32_e32 v224, v93, v93
	v_mul_f32_e32 v225, v95, v95
	v_fmac_f32_e32 v224, v92, v92
	v_fmac_f32_e32 v225, v94, v94
	global_store_dwordx2 v231, v[222:223], s[20:21] offset:32
	v_add_f32_e32 v227, v224, v225
	v_pk_add_f32 v[90:91], v[90:91], v[200:201]
	v_pk_add_f32 v[88:89], v[88:89], v[198:199]
	v_cvt_pk_bf16_f32 v222, v88, v89
	v_cvt_pk_bf16_f32 v223, v90, v91
	v_mul_f32_e32 v224, v89, v89
	v_mul_f32_e32 v225, v91, v91
	v_fmac_f32_e32 v224, v88, v88
	v_fmac_f32_e32 v225, v90, v90
	global_store_dwordx2 v231, v[222:223], s[20:21] offset:256
	v_add_f32_e32 v228, v224, v225
	v_pk_add_f32 v[86:87], v[86:87], v[204:205]
	v_pk_add_f32 v[84:85], v[84:85], v[202:203]
	v_cvt_pk_bf16_f32 v222, v84, v85
	v_cvt_pk_bf16_f32 v223, v86, v87
	v_mul_f32_e32 v224, v85, v85
	v_mul_f32_e32 v225, v87, v87
	v_fmac_f32_e32 v224, v84, v84
	v_fmac_f32_e32 v225, v86, v86
	global_store_dwordx2 v231, v[222:223], s[20:21] offset:288
	v_add_f32_e32 v229, v224, v225
	v_add_f32_e32 v226, v226, v227
	v_add_f32_e32 v226, v226, v228
	v_add_f32_e32 v226, v226, v229
	ds_bpermute_b32 v224, v146, v226
	v_add_u32_e32 v225, 0x20, v144
	v_lshlrev_b32_e32 v225, 2, v225
	s_waitcnt lgkmcnt(0)
	v_add_f32_e32 v226, v226, v224
	ds_bpermute_b32 v224, v147, v226
	s_waitcnt lgkmcnt(0)
	v_add_f32_e32 v226, v226, v224
	s_and_b64 exec, exec, s[2:3]
	global_atomic_add_f32 v225, v226, s[22:23]
	s_mov_b64 exec, s[0:1]
	v_add_u32_e32 v230, 0x140000, v3
	global_load_dwordx4 v[190:193], v230, s[56:57]
	global_load_dwordx4 v[194:197], v230, s[56:57] offset:64
	global_load_dwordx4 v[198:201], v230, s[56:57] offset:512
	global_load_dwordx4 v[202:205], v230, s[56:57] offset:576
	s_waitcnt vmcnt(24)
	v_add_u32_e32 v231, 0x30000, v1
	v_pk_add_f32 v[82:83], v[82:83], v[208:209]
	v_pk_add_f32 v[80:81], v[80:81], v[206:207]
	v_cvt_pk_bf16_f32 v222, v80, v81
	v_cvt_pk_bf16_f32 v223, v82, v83
	v_mul_f32_e32 v224, v81, v81
	v_mul_f32_e32 v225, v83, v83
	v_fmac_f32_e32 v224, v80, v80
	v_fmac_f32_e32 v225, v82, v82
	global_store_dwordx2 v231, v[222:223], s[20:21]
	v_add_f32_e32 v226, v224, v225
	v_pk_add_f32 v[78:79], v[78:79], v[212:213]
	v_pk_add_f32 v[76:77], v[76:77], v[210:211]
	v_cvt_pk_bf16_f32 v222, v76, v77
	v_cvt_pk_bf16_f32 v223, v78, v79
	v_mul_f32_e32 v224, v77, v77
	v_mul_f32_e32 v225, v79, v79
	v_fmac_f32_e32 v224, v76, v76
	v_fmac_f32_e32 v225, v78, v78
	global_store_dwordx2 v231, v[222:223], s[20:21] offset:32
	v_add_f32_e32 v227, v224, v225
	v_pk_add_f32 v[74:75], v[74:75], v[216:217]
	v_pk_add_f32 v[72:73], v[72:73], v[214:215]
	v_cvt_pk_bf16_f32 v222, v72, v73
	v_cvt_pk_bf16_f32 v223, v74, v75
	v_mul_f32_e32 v224, v73, v73
	v_mul_f32_e32 v225, v75, v75
	v_fmac_f32_e32 v224, v72, v72
	v_fmac_f32_e32 v225, v74, v74
	global_store_dwordx2 v231, v[222:223], s[20:21] offset:256
	v_add_f32_e32 v228, v224, v225
	v_pk_add_f32 v[70:71], v[70:71], v[220:221]
	v_pk_add_f32 v[68:69], v[68:69], v[218:219]
	v_cvt_pk_bf16_f32 v222, v68, v69
	v_cvt_pk_bf16_f32 v223, v70, v71
	v_mul_f32_e32 v224, v69, v69
	v_mul_f32_e32 v225, v71, v71
	v_fmac_f32_e32 v224, v68, v68
	v_fmac_f32_e32 v225, v70, v70
	global_store_dwordx2 v231, v[222:223], s[20:21] offset:288
	v_add_f32_e32 v229, v224, v225
	v_add_f32_e32 v226, v226, v227
	v_add_f32_e32 v226, v226, v228
	v_add_f32_e32 v226, v226, v229
	ds_bpermute_b32 v224, v146, v226
	v_add_u32_e32 v225, 0x30, v144
	v_lshlrev_b32_e32 v225, 2, v225
	s_waitcnt lgkmcnt(0)
	v_add_f32_e32 v226, v226, v224
	ds_bpermute_b32 v224, v147, v226
	s_waitcnt lgkmcnt(0)
	v_add_f32_e32 v226, v226, v224
	s_and_b64 exec, exec, s[2:3]
	global_atomic_add_f32 v225, v226, s[22:23]
	s_mov_b64 exec, s[0:1]
	v_add_u32_e32 v230, 0x160000, v3
	global_load_dwordx4 v[206:209], v230, s[56:57]
	global_load_dwordx4 v[210:213], v230, s[56:57] offset:64
	global_load_dwordx4 v[214:217], v230, s[56:57] offset:512
	global_load_dwordx4 v[218:221], v230, s[56:57] offset:576
	s_waitcnt vmcnt(24)
	v_add_u32_e32 v231, 0x80000, v1
	v_pk_add_f32 v[66:67], v[66:67], v[158:159]
	v_pk_add_f32 v[64:65], v[64:65], v[156:157]
	v_cvt_pk_bf16_f32 v222, v64, v65
	v_cvt_pk_bf16_f32 v223, v66, v67
	v_mul_f32_e32 v224, v65, v65
	v_mul_f32_e32 v225, v67, v67
	v_fmac_f32_e32 v224, v64, v64
	v_fmac_f32_e32 v225, v66, v66
	global_store_dwordx2 v231, v[222:223], s[20:21]
	v_add_f32_e32 v226, v224, v225
	v_pk_add_f32 v[62:63], v[62:63], v[162:163]
	v_pk_add_f32 v[60:61], v[60:61], v[160:161]
	v_cvt_pk_bf16_f32 v222, v60, v61
	v_cvt_pk_bf16_f32 v223, v62, v63
	v_mul_f32_e32 v224, v61, v61
	v_mul_f32_e32 v225, v63, v63
	v_fmac_f32_e32 v224, v60, v60
	v_fmac_f32_e32 v225, v62, v62
	global_store_dwordx2 v231, v[222:223], s[20:21] offset:32
	v_add_f32_e32 v227, v224, v225
	v_pk_add_f32 v[58:59], v[58:59], v[166:167]
	v_pk_add_f32 v[56:57], v[56:57], v[164:165]
	v_cvt_pk_bf16_f32 v222, v56, v57
	v_cvt_pk_bf16_f32 v223, v58, v59
	v_mul_f32_e32 v224, v57, v57
	v_mul_f32_e32 v225, v59, v59
	v_fmac_f32_e32 v224, v56, v56
	v_fmac_f32_e32 v225, v58, v58
	global_store_dwordx2 v231, v[222:223], s[20:21] offset:256
	v_add_f32_e32 v228, v224, v225
	v_pk_add_f32 v[54:55], v[54:55], v[170:171]
	v_pk_add_f32 v[52:53], v[52:53], v[168:169]
	v_cvt_pk_bf16_f32 v222, v52, v53
	v_cvt_pk_bf16_f32 v223, v54, v55
	v_mul_f32_e32 v224, v53, v53
	v_mul_f32_e32 v225, v55, v55
	v_fmac_f32_e32 v224, v52, v52
	v_fmac_f32_e32 v225, v54, v54
	global_store_dwordx2 v231, v[222:223], s[20:21] offset:288
	v_add_f32_e32 v229, v224, v225
	v_add_f32_e32 v226, v226, v227
	v_add_f32_e32 v226, v226, v228
	v_add_f32_e32 v226, v226, v229
	ds_bpermute_b32 v224, v146, v226
	v_add_u32_e32 v225, 0x80, v144
	v_lshlrev_b32_e32 v225, 2, v225
	s_waitcnt lgkmcnt(0)
	v_add_f32_e32 v226, v226, v224
	ds_bpermute_b32 v224, v147, v226
	s_waitcnt lgkmcnt(0)
	v_add_f32_e32 v226, v226, v224
	s_and_b64 exec, exec, s[2:3]
	global_atomic_add_f32 v225, v226, s[22:23]
	s_mov_b64 exec, s[0:1]
	s_waitcnt vmcnt(20)
	v_add_u32_e32 v231, 0x90000, v1
	v_pk_add_f32 v[50:51], v[50:51], v[176:177]
	v_pk_add_f32 v[48:49], v[48:49], v[174:175]
	v_cvt_pk_bf16_f32 v222, v48, v49
	v_cvt_pk_bf16_f32 v223, v50, v51
	v_mul_f32_e32 v224, v49, v49
	v_mul_f32_e32 v225, v51, v51
	v_fmac_f32_e32 v224, v48, v48
	v_fmac_f32_e32 v225, v50, v50
	global_store_dwordx2 v231, v[222:223], s[20:21]
	v_add_f32_e32 v226, v224, v225
	v_pk_add_f32 v[46:47], v[46:47], v[180:181]
	v_pk_add_f32 v[44:45], v[44:45], v[178:179]
	v_cvt_pk_bf16_f32 v222, v44, v45
	v_cvt_pk_bf16_f32 v223, v46, v47
	v_mul_f32_e32 v224, v45, v45
	v_mul_f32_e32 v225, v47, v47
	v_fmac_f32_e32 v224, v44, v44
	v_fmac_f32_e32 v225, v46, v46
	global_store_dwordx2 v231, v[222:223], s[20:21] offset:32
	v_add_f32_e32 v227, v224, v225
	v_pk_add_f32 v[42:43], v[42:43], v[184:185]
	v_pk_add_f32 v[40:41], v[40:41], v[182:183]
	v_cvt_pk_bf16_f32 v222, v40, v41
	v_cvt_pk_bf16_f32 v223, v42, v43
	v_mul_f32_e32 v224, v41, v41
	v_mul_f32_e32 v225, v43, v43
	v_fmac_f32_e32 v224, v40, v40
	v_fmac_f32_e32 v225, v42, v42
	global_store_dwordx2 v231, v[222:223], s[20:21] offset:256
	v_add_f32_e32 v228, v224, v225
	v_pk_add_f32 v[38:39], v[38:39], v[188:189]
	v_pk_add_f32 v[36:37], v[36:37], v[186:187]
	v_cvt_pk_bf16_f32 v222, v36, v37
	v_cvt_pk_bf16_f32 v223, v38, v39
	v_mul_f32_e32 v224, v37, v37
	v_mul_f32_e32 v225, v39, v39
	v_fmac_f32_e32 v224, v36, v36
	v_fmac_f32_e32 v225, v38, v38
	global_store_dwordx2 v231, v[222:223], s[20:21] offset:288
	v_add_f32_e32 v229, v224, v225
	v_add_f32_e32 v226, v226, v227
	v_add_f32_e32 v226, v226, v228
	v_add_f32_e32 v226, v226, v229
	ds_bpermute_b32 v224, v146, v226
	v_add_u32_e32 v225, 0x90, v144
	v_lshlrev_b32_e32 v225, 2, v225
	s_waitcnt lgkmcnt(0)
	v_add_f32_e32 v226, v226, v224
	ds_bpermute_b32 v224, v147, v226
	s_waitcnt lgkmcnt(0)
	v_add_f32_e32 v226, v226, v224
	s_and_b64 exec, exec, s[2:3]
	global_atomic_add_f32 v225, v226, s[22:23]
	s_mov_b64 exec, s[0:1]
	s_waitcnt vmcnt(16)
	v_add_u32_e32 v231, 0xa0000, v1
	v_pk_add_f32 v[34:35], v[34:35], v[192:193]
	v_pk_add_f32 v[32:33], v[32:33], v[190:191]
	v_cvt_pk_bf16_f32 v222, v32, v33
	v_cvt_pk_bf16_f32 v223, v34, v35
	v_mul_f32_e32 v224, v33, v33
	v_mul_f32_e32 v225, v35, v35
	v_fmac_f32_e32 v224, v32, v32
	v_fmac_f32_e32 v225, v34, v34
	global_store_dwordx2 v231, v[222:223], s[20:21]
	v_add_f32_e32 v226, v224, v225
	v_pk_add_f32 v[30:31], v[30:31], v[196:197]
	v_pk_add_f32 v[28:29], v[28:29], v[194:195]
	v_cvt_pk_bf16_f32 v222, v28, v29
	v_cvt_pk_bf16_f32 v223, v30, v31
	v_mul_f32_e32 v224, v29, v29
	v_mul_f32_e32 v225, v31, v31
	v_fmac_f32_e32 v224, v28, v28
	v_fmac_f32_e32 v225, v30, v30
	global_store_dwordx2 v231, v[222:223], s[20:21] offset:32
	v_add_f32_e32 v227, v224, v225
	v_pk_add_f32 v[26:27], v[26:27], v[200:201]
	v_pk_add_f32 v[24:25], v[24:25], v[198:199]
	v_cvt_pk_bf16_f32 v222, v24, v25
	v_cvt_pk_bf16_f32 v223, v26, v27
	v_mul_f32_e32 v224, v25, v25
	v_mul_f32_e32 v225, v27, v27
	v_fmac_f32_e32 v224, v24, v24
	v_fmac_f32_e32 v225, v26, v26
	global_store_dwordx2 v231, v[222:223], s[20:21] offset:256
	v_add_f32_e32 v228, v224, v225
	v_pk_add_f32 v[22:23], v[22:23], v[204:205]
	v_pk_add_f32 v[20:21], v[20:21], v[202:203]
	v_cvt_pk_bf16_f32 v222, v20, v21
	v_cvt_pk_bf16_f32 v223, v22, v23
	v_mul_f32_e32 v224, v21, v21
	v_mul_f32_e32 v225, v23, v23
	v_fmac_f32_e32 v224, v20, v20
	v_fmac_f32_e32 v225, v22, v22
	global_store_dwordx2 v231, v[222:223], s[20:21] offset:288
	v_add_f32_e32 v229, v224, v225
	v_add_f32_e32 v226, v226, v227
	v_add_f32_e32 v226, v226, v228
	v_add_f32_e32 v226, v226, v229
	ds_bpermute_b32 v224, v146, v226
	v_add_u32_e32 v225, 0xa0, v144
	v_lshlrev_b32_e32 v225, 2, v225
	s_waitcnt lgkmcnt(0)
	v_add_f32_e32 v226, v226, v224
	ds_bpermute_b32 v224, v147, v226
	s_waitcnt lgkmcnt(0)
	v_add_f32_e32 v226, v226, v224
	s_and_b64 exec, exec, s[2:3]
	global_atomic_add_f32 v225, v226, s[22:23]
	s_mov_b64 exec, s[0:1]
	s_waitcnt vmcnt(12)
	v_add_u32_e32 v231, 0xb0000, v1
	v_pk_add_f32 v[18:19], v[18:19], v[208:209]
	v_pk_add_f32 v[16:17], v[16:17], v[206:207]
	v_cvt_pk_bf16_f32 v222, v16, v17
	v_cvt_pk_bf16_f32 v223, v18, v19
	v_mul_f32_e32 v224, v17, v17
	v_mul_f32_e32 v225, v19, v19
	v_fmac_f32_e32 v224, v16, v16
	v_fmac_f32_e32 v225, v18, v18
	global_store_dwordx2 v231, v[222:223], s[20:21]
	v_add_f32_e32 v226, v224, v225
	v_pk_add_f32 v[14:15], v[14:15], v[212:213]
	v_pk_add_f32 v[12:13], v[12:13], v[210:211]
	v_cvt_pk_bf16_f32 v222, v12, v13
	v_cvt_pk_bf16_f32 v223, v14, v15
	v_mul_f32_e32 v224, v13, v13
	v_mul_f32_e32 v225, v15, v15
	v_fmac_f32_e32 v224, v12, v12
	v_fmac_f32_e32 v225, v14, v14
	global_store_dwordx2 v231, v[222:223], s[20:21] offset:32
	v_add_f32_e32 v227, v224, v225
	v_pk_add_f32 v[10:11], v[10:11], v[216:217]
	v_pk_add_f32 v[8:9], v[8:9], v[214:215]
	v_cvt_pk_bf16_f32 v222, v8, v9
	v_cvt_pk_bf16_f32 v223, v10, v11
	v_mul_f32_e32 v224, v9, v9
	v_mul_f32_e32 v225, v11, v11
	v_fmac_f32_e32 v224, v8, v8
	v_fmac_f32_e32 v225, v10, v10
	global_store_dwordx2 v231, v[222:223], s[20:21] offset:256
	v_add_f32_e32 v228, v224, v225
	v_pk_add_f32 v[6:7], v[6:7], v[220:221]
	v_pk_add_f32 v[4:5], v[4:5], v[218:219]
	v_cvt_pk_bf16_f32 v222, v4, v5
	v_cvt_pk_bf16_f32 v223, v6, v7
	v_mul_f32_e32 v224, v5, v5
	v_mul_f32_e32 v225, v7, v7
	v_fmac_f32_e32 v224, v4, v4
	v_fmac_f32_e32 v225, v6, v6
	global_store_dwordx2 v231, v[222:223], s[20:21] offset:288
	v_add_f32_e32 v229, v224, v225
	v_add_f32_e32 v226, v226, v227
	v_add_f32_e32 v226, v226, v228
	v_add_f32_e32 v226, v226, v229
	ds_bpermute_b32 v224, v146, v226
	v_add_u32_e32 v225, 0xb0, v144
	v_lshlrev_b32_e32 v225, 2, v225
	s_waitcnt lgkmcnt(0)
	v_add_f32_e32 v226, v226, v224
	ds_bpermute_b32 v224, v147, v226
	s_waitcnt lgkmcnt(0)
	v_add_f32_e32 v226, v226, v224
	s_and_b64 exec, exec, s[2:3]
	global_atomic_add_f32 v225, v226, s[22:23]
	s_mov_b64 exec, s[0:1]
